# GEMM-up epilogue: HALO/HEAD row stores issued behind the conv-weight wait instead of in front of it
# baseline (speedup 1.0000x reference)
; #define LAS __attribute__((address_space(3)))
;     __device__ __forceinline__ void operator()(const f32x4 (&acc)[2][2][4][2], const pg8::Unit& u, int wr, int wc, int fr, int fq) const {
;         asm volatile("s_nop 7\n\ts_nop 7\n\ts_nop 7" ::: "memory");
;         const int cc0 = wc * 32 + 8 * fq;
;         if (fr >= 14) {
; #pragma unroll
;             for (int ai = 0; ai < 2; ++ai)
; #pragma unroll
;                 for (int bj = 0; bj < 2; ++bj)
; #pragma unroll
;                     for (int n = 0; n < 2; ++n) *(LAS f32x4*)(xb + ((2 * ai + wr) * 2 + (fr - 14)) * 256 + bj * 128 + cc0 + 4 * n) = acc[ai][bj][3][n];
;             if (wr == 1) {
; #pragma unroll
;                 for (int bj = 0; bj < 2; ++bj)
; #pragma unroll
;                     for (int n = 0; n < 2; ++n) *(f32x4*)(halo + ((size_t)u.pm * 2 + (fr - 14)) * UPW + u.pn * 256 + bj * 128 + cc0 + 4 * n) = acc[1][bj][3][n];
;             }
;         }
;         if (wr == 0 && fr < 2) {
; #pragma unroll
;             for (int bj = 0; bj < 2; ++bj)
; #pragma unroll
;                 for (int n = 0; n < 2; ++n) *(f32x4*)(head + ((size_t)u.pm * 2 + fr) * UPW + u.pn * 256 + bj * 128 + cc0 + 4 * n) = acc[0][bj][0][n];
;         }
;         asm volatile("s_waitcnt lgkmcnt(0)" ::: "memory"); __builtin_amdgcn_s_barrier(); asm volatile("" ::: "memory");
;     ...
;             const f32x4 g0w = *(const f32x4*)(cw + jg), g1w = *(const f32x4*)(cw + UPW + jg), g2w = *(const f32x4*)(cw + 2 * UPW + jg), gb = *(const f32x4*)(cb + jg);
;             const f32x4 u0w = *(const f32x4*)(cw + DFF + jg), u1w = *(const f32x4*)(cw + UPW + DFF + jg), u2w = *(const f32x4*)(cw + 2 * UPW + DFF + jg), ub = *(const f32x4*)(cb + DFF + jg);
.LBB0_931:
	s_nop 7
	s_nop 7
	s_nop 7
	v_cndmask_b32_e64 v112, 0, 1, s[12:13]
	v_cmp_ne_u32_e64 s[6:7], 1, v112
	s_lshl_b32 s54, s76, 7
	v_or_b32_e32 v244, s54, v192
	v_lshlrev_b32_e32 v244, 2, v244
	v_readlane_b32 s84, v245, 13
	v_readlane_b32 s85, v245, 14
	v_readlane_b32 s86, v245, 15
	v_readlane_b32 s87, v245, 16
	s_nop 4
	global_load_dwordx4 v[148:151], v244, s[34:35]
	global_load_dwordx4 v[156:159], v244, s[86:87]
	global_load_dwordx4 v[132:135], v244, s[40:41]
	global_load_dwordx4 v[140:143], v244, s[42:43]
	global_load_dwordx4 v[152:155], v244, s[30:31]
	global_load_dwordx4 v[128:131], v244, s[38:39]
	global_load_dwordx4 v[144:147], v244, s[84:85]
	global_load_dwordx4 v[136:139], v244, s[36:37]
	v_cmp_eq_u32_e64 s[80:81], 15, v190
	s_and_saveexec_b64 s[8:9], s[80:81]
	s_cbranch_execz .Lupc2_a
	v_add_u32_e32 v112, 0xfffffc00, v213
	ds_write_b128 v112, v[108:111]
	ds_write_b128 v112, v[104:107] offset:1024
	ds_write_b128 v112, v[44:47] offset:16
	ds_write_b128 v112, v[40:43] offset:1040
	ds_write_b128 v112, v[100:103] offset:512
	ds_write_b128 v112, v[96:99] offset:1536
	ds_write_b128 v112, v[36:39] offset:528
	ds_write_b128 v112, v[32:35] offset:1552
	ds_write_b128 v112, v[76:79] offset:4096
	ds_write_b128 v112, v[72:75] offset:5120
	ds_write_b128 v112, v[12:15] offset:4112
	ds_write_b128 v112, v[8:11] offset:5136
	ds_write_b128 v112, v[68:71] offset:4608
	ds_write_b128 v112, v[64:67] offset:5632
	ds_write_b128 v112, v[4:7] offset:4624
	ds_write_b128 v112, v[0:3] offset:5648
.Lupc2_a:
	s_or_b64 exec, exec, s[8:9]
	v_cmp_eq_u32_e64 s[80:81], 0, v190
	s_and_b64 s[80:81], s[80:81], s[22:23]
	s_and_saveexec_b64 s[8:9], s[80:81]
	s_cbranch_execz .Lupc2_b
.Lupc2_b:
	s_or_b64 exec, exec, s[8:9]
	s_lshl_b32 s54, s76, 7
	s_waitcnt lgkmcnt(0)
	s_barrier
	s_lshl_b32 s2, s52, 8
	v_mad_u32_u24 v243, v190, 3, v193
	v_add_u32_e32 v243, s2, v243
	v_mul_u32_u24_e32 v243, 0x2c00, v243
	s_lshl_b32 s2, s54, 1
	v_add3_u32 v243, v243, s2, v188
	v_mov_b32_e32 v126, 0xbfb8aa3b
	v_mov_b32_e32 v127, 0xbfb8aa3b
	v_cmp_ne_u32_e64 s[78:79], 0, v190
	s_nop 3
	s_or_b64 s[78:79], s[78:79], s[24:25]
	v_mov_b32_e32 v172, 0
	v_mov_b32_e32 v173, 0
	v_mov_b32_e32 v174, 0
	v_mov_b32_e32 v175, 0
	v_mov_b32_e32 v164, 0
	v_mov_b32_e32 v165, 0
	v_mov_b32_e32 v166, 0
	v_mov_b32_e32 v167, 0
	v_mov_b32_e32 v176, 0
	v_mov_b32_e32 v177, 0
	v_mov_b32_e32 v178, 0
	v_mov_b32_e32 v179, 0
	v_mov_b32_e32 v168, 0
	v_mov_b32_e32 v169, 0
	v_mov_b32_e32 v170, 0
	v_mov_b32_e32 v171, 0
	s_andn2_b64 vcc, exec, s[24:25]
	s_cbranch_vccnz .Lupc2_nocarry00
	ds_read_b128 v[172:175], v215 offset:1024
	ds_read_b128 v[164:167], v215 offset:1536
	ds_read_b128 v[176:179], v215
	ds_read_b128 v[168:171], v215 offset:512
.Lupc2_nocarry00:
	s_waitcnt vmcnt(0) lgkmcnt(0)
	v_cmp_eq_u32_e64 s[80:81], 15, v190
	s_and_saveexec_b64 s[8:9], s[80:81]
	s_cbranch_execz .Lupc3_a
	s_and_b64 vcc, exec, s[6:7]
	s_cbranch_vccnz .Lupc3_a
	s_mov_b32 s98, s52
	s_ashr_i32 s99, s52, 31
	v_lshl_add_u64 v[112:113], s[98:99], 1, v[194:195]
	v_mov_b64_e32 v[126:127], s[18:19]
	s_lshl_b32 s100, s76, 8
	v_mad_u64_u32 v[126:127], vcc, v112, s74, v[126:127]
	s_ashr_i32 s101, s100, 31
	v_mad_i32_i24 v127, v113, s74, v127
	v_lshl_add_u64 v[112:113], s[100:101], 2, v[126:127]
	v_lshlrev_b32_e32 v126, 2, v192
	v_mov_b32_e32 v127, v189
	v_lshl_add_u64 v[112:113], v[112:113], 0, v[126:127]
	s_mov_b32 s82, 0xffff5000
	s_mov_b32 s83, -1
	v_lshl_add_u64 v[126:127], v[112:113], 0, s[82:83]
	global_store_dwordx4 v[126:127], v[76:79], off
	global_store_dwordx4 v[112:113], v[72:75], off
	global_store_dwordx4 v[126:127], v[12:15], off offset:16
	global_store_dwordx4 v[112:113], v[8:11], off offset:16
	global_store_dwordx4 v[126:127], v[68:71], off offset:512
	global_store_dwordx4 v[112:113], v[64:67], off offset:512
	global_store_dwordx4 v[126:127], v[4:7], off offset:528
	global_store_dwordx4 v[112:113], v[0:3], off offset:528
.Lupc3_a:
	s_or_b64 exec, exec, s[8:9]
	v_cmp_eq_u32_e64 s[80:81], 0, v190
	s_and_b64 s[80:81], s[80:81], s[22:23]
	s_and_saveexec_b64 s[8:9], s[80:81]
	s_cbranch_execz .Lupc3_b
	v_lshl_or_b32 v126, s52, 1, v190
	v_mov_b64_e32 v[112:113], s[16:17]
	s_ashr_i32 s32, s52, 31
	s_lshl_b32 s100, s76, 8
	v_mad_u64_u32 v[112:113], vcc, v126, s74, v[112:113]
	s_ashr_i32 s101, s100, 31
	v_mad_i32_i24 v113, s32, v225, v113
	v_lshl_add_u64 v[112:113], s[100:101], 2, v[112:113]
	v_lshlrev_b32_e32 v126, 2, v192
	v_mov_b32_e32 v127, v189
	v_lshl_add_u64 v[112:113], v[112:113], 0, v[126:127]
	s_mov_b32 s82, 0xb000
	s_mov_b32 s83, 0
	v_lshl_add_u64 v[126:127], v[112:113], 0, s[82:83]
	global_store_dwordx4 v[112:113], v[160:163], off
	global_store_dwordx4 v[126:127], v[122:125], off
	global_store_dwordx4 v[112:113], v[60:63], off offset:16
	global_store_dwordx4 v[126:127], v[52:55], off offset:16
	global_store_dwordx4 v[112:113], v[114:117], off offset:512
	global_store_dwordx4 v[126:127], v[118:121], off offset:512
	global_store_dwordx4 v[112:113], v[56:59], off offset:528
	global_store_dwordx4 v[126:127], v[48:51], off offset:528
; #define LAS __attribute__((address_space(3)))
; __device__ __forceinline__ unsigned cvt_pk_bf16(float lo, float hi) { unsigned r; asm volatile("v_cvt_pk_bf16_f32 %0, %1, %2" : "=v"(r) : "v"(lo), "v"(hi)); return r; }
; __device__ __forceinline__ float fast_silu(float x) { return x * fast_sigmoid(x); }
; __device__ __forceinline__ float dpp_shr1(float old, float src) { return __int_as_float(__builtin_amdgcn_update_dpp(__float_as_int(old), __float_as_int(src), 0x111, 0xf, 0xf, false)); }
;     __device__ __forceinline__ void operator()(const f32x4 (&acc)[2][2][4][2], const pg8::Unit& u, int wr, int wc, int fr, int fq) const {
;     ...
; #pragma unroll
;             for (int ai = 0; ai < 2; ++ai) {
;                 const int gi = 2 * ai + wr;
;                 f32x4 pg1 = (f32x4){0.f, 0.f, 0.f, 0.f}, pg2 = pg1, pu1 = pg1, pu2 = pg1;
;                 if (gi > 0) {
;                     const LAS float* xp = xb + ((gi - 1) * 2) * 256 + cc0 + 4 * n;
;                     pg1 = *(const LAS f32x4*)(xp + 256); pu1 = *(const LAS f32x4*)(xp + 256 + 128);
;                     pg2 = *(const LAS f32x4*)(xp + (fr & 1) * 256); pu2 = *(const LAS f32x4*)(xp + (fr & 1) * 256 + 128);
;                 }
; #pragma unroll
;                 for (int m = 0; m < 4; ++m) {
;                     float a[4];
; #pragma unroll
;                     for (int e = 0; e < 4; ++e) {
;                         const float gc = acc[ai][0][m][n][e], uc = acc[ai][1][m][n][e];
;                         float og1, og2, ou1, ou2;
;                         if (m == 0) { og1 = pg1[e]; og2 = pg2[e]; ou1 = pu1[e]; ou2 = pu2[e]; }
;                         else { const float gp = acc[ai][0][m - 1][n][e], up = acc[ai][1][m - 1][n][e]; og1 = dpp_ror1(gp); og2 = dpp_ror2(gp); ou1 = dpp_ror1(up); ou2 = dpp_ror2(up); }
;                         const float gm1 = dpp_shr1(og1, gc), gm2 = dpp_shr2(og2, gc), um1 = dpp_shr1(ou1, uc), um2 = dpp_shr2(ou2, uc);
;                         const float yg = g0w[e] * gm2 + g1w[e] * gm1 + g2w[e] * gc + gb[e];
;                         const float yu = u0w[e] * um2 + u1w[e] * um1 + u2w[e] * uc + ub[e];
;                         a[e] = fast_silu(yg) * yu;
;                     }
;                     u32x2 pk; pk.x = cvt_pk_bf16(a[0], a[1]); pk.y = cvt_pk_bf16(a[2], a[3]);
.Lupc3_b:
	s_or_b64 exec, exec, s[8:9]
	s_nop 4
	v_mov_b32_e32 v126, 0xbfb8aa3b
	v_mov_b32_e32 v127, 0xbfb8aa3b
	v_mov_b32_dpp v172, v104 row_shr:1 row_mask:0xf bank_mask:0xf
	v_mov_b32_dpp v176, v108 row_shr:1 row_mask:0xf bank_mask:0xf
	v_mov_b32_dpp v164, v96 row_shr:1 row_mask:0xf bank_mask:0xf
	v_mov_b32_dpp v168, v100 row_shr:1 row_mask:0xf bank_mask:0xf
	v_mov_b32_dpp v173, v105 row_shr:1 row_mask:0xf bank_mask:0xf
	v_mov_b32_dpp v177, v109 row_shr:1 row_mask:0xf bank_mask:0xf
	v_mov_b32_dpp v165, v97 row_shr:1 row_mask:0xf bank_mask:0xf
	v_mov_b32_dpp v169, v101 row_shr:1 row_mask:0xf bank_mask:0xf
	v_mov_b32_dpp v174, v106 row_shr:1 row_mask:0xf bank_mask:0xf
	v_mov_b32_dpp v178, v110 row_shr:1 row_mask:0xf bank_mask:0xf
	v_mov_b32_dpp v166, v98 row_shr:1 row_mask:0xf bank_mask:0xf
	v_mov_b32_dpp v170, v102 row_shr:1 row_mask:0xf bank_mask:0xf
	v_mov_b32_dpp v175, v107 row_shr:1 row_mask:0xf bank_mask:0xf
	v_mov_b32_dpp v179, v111 row_shr:1 row_mask:0xf bank_mask:0xf
	v_mov_b32_dpp v167, v99 row_shr:1 row_mask:0xf bank_mask:0xf
	v_mov_b32_dpp v171, v103 row_shr:1 row_mask:0xf bank_mask:0xf
	v_pk_fma_f32 v[204:205], v[148:149], v[104:105], v[156:157]
	v_pk_fma_f32 v[112:113], v[132:133], v[96:97], v[140:141]
	v_pk_fma_f32 v[206:207], v[150:151], v[106:107], v[158:159]
	v_pk_fma_f32 v[210:211], v[134:135], v[98:99], v[142:143]
	v_pk_fma_f32 v[204:205], v[152:153], v[108:109], v[204:205]
	v_pk_fma_f32 v[112:113], v[128:129], v[100:101], v[112:113]
	v_pk_fma_f32 v[206:207], v[154:155], v[110:111], v[206:207]
	v_pk_fma_f32 v[210:211], v[130:131], v[102:103], v[210:211]
	v_pk_fma_f32 v[204:205], v[144:145], v[122:123], v[204:205]
	v_pk_fma_f32 v[112:113], v[136:137], v[118:119], v[112:113]
	v_pk_fma_f32 v[206:207], v[146:147], v[124:125], v[206:207]
	v_pk_fma_f32 v[210:211], v[138:139], v[120:121], v[210:211]
	v_pk_mul_f32 v[226:227], v[204:205], v[126:127]
	v_pk_mul_f32 v[228:229], v[206:207], v[126:127]
	v_exp_f32_e32 v226, v226
	v_exp_f32_e32 v227, v227
	v_exp_f32_e32 v228, v228
	v_exp_f32_e32 v229, v229
	s_nop 0
	v_pk_add_f32 v[226:227], v[226:227], 1.0 op_sel_hi:[1,0]
	v_pk_add_f32 v[228:229], v[228:229], 1.0 op_sel_hi:[1,0]
	v_rcp_f32_e32 v226, v226
	v_rcp_f32_e32 v227, v227
	v_rcp_f32_e32 v228, v228
	v_rcp_f32_e32 v229, v229
	s_nop 0
	v_pk_mul_f32 v[204:205], v[204:205], v[226:227]
	v_pk_mul_f32 v[206:207], v[206:207], v[228:229]
	v_pk_mul_f32 v[204:205], v[204:205], v[112:113]
	v_pk_mul_f32 v[206:207], v[206:207], v[210:211]
	v_cvt_pk_bf16_f32 v104, v204, v205
	v_cvt_pk_bf16_f32 v105, v206, v207
	v_pk_fma_f32 v[204:205], v[148:149], v[108:109], v[156:157]
	v_pk_fma_f32 v[112:113], v[132:133], v[100:101], v[140:141]
	v_pk_fma_f32 v[206:207], v[150:151], v[110:111], v[158:159]
	v_pk_fma_f32 v[210:211], v[134:135], v[102:103], v[142:143]
	v_pk_fma_f32 v[204:205], v[152:153], v[122:123], v[204:205]
	v_pk_fma_f32 v[112:113], v[128:129], v[118:119], v[112:113]
	v_pk_fma_f32 v[206:207], v[154:155], v[124:125], v[206:207]
	v_pk_fma_f32 v[210:211], v[130:131], v[120:121], v[210:211]
	v_pk_fma_f32 v[204:205], v[144:145], v[160:161], v[204:205]
	v_pk_fma_f32 v[112:113], v[136:137], v[114:115], v[112:113]
	v_pk_fma_f32 v[206:207], v[146:147], v[162:163], v[206:207]
	v_pk_fma_f32 v[210:211], v[138:139], v[116:117], v[210:211]
	v_pk_mul_f32 v[226:227], v[204:205], v[126:127]
	v_pk_mul_f32 v[228:229], v[206:207], v[126:127]
	v_exp_f32_e32 v226, v226
	v_exp_f32_e32 v227, v227
	v_exp_f32_e32 v228, v228
	v_exp_f32_e32 v229, v229
	s_nop 0
	v_pk_add_f32 v[226:227], v[226:227], 1.0 op_sel_hi:[1,0]
	v_pk_add_f32 v[228:229], v[228:229], 1.0 op_sel_hi:[1,0]
	v_rcp_f32_e32 v226, v226
	v_rcp_f32_e32 v227, v227
	v_rcp_f32_e32 v228, v228
	v_rcp_f32_e32 v229, v229
	s_nop 0
	v_pk_mul_f32 v[204:205], v[204:205], v[226:227]
	v_pk_mul_f32 v[206:207], v[206:207], v[228:229]
	v_pk_mul_f32 v[204:205], v[204:205], v[112:113]
	v_pk_mul_f32 v[206:207], v[206:207], v[210:211]
	v_cvt_pk_bf16_f32 v108, v204, v205
	v_cvt_pk_bf16_f32 v109, v206, v207
	v_pk_fma_f32 v[204:205], v[148:149], v[122:123], v[156:157]
	v_pk_fma_f32 v[112:113], v[132:133], v[118:119], v[140:141]
	v_pk_fma_f32 v[206:207], v[150:151], v[124:125], v[158:159]
	v_pk_fma_f32 v[210:211], v[134:135], v[120:121], v[142:143]
	v_pk_fma_f32 v[204:205], v[152:153], v[160:161], v[204:205]
	v_pk_fma_f32 v[112:113], v[128:129], v[114:115], v[112:113]
	v_pk_fma_f32 v[206:207], v[154:155], v[162:163], v[206:207]
	v_pk_fma_f32 v[210:211], v[130:131], v[116:117], v[210:211]
	v_pk_fma_f32 v[204:205], v[144:145], v[172:173], v[204:205]
	v_pk_fma_f32 v[112:113], v[136:137], v[164:165], v[112:113]
	v_pk_fma_f32 v[206:207], v[146:147], v[174:175], v[206:207]
	v_pk_fma_f32 v[210:211], v[138:139], v[166:167], v[210:211]
	v_pk_mul_f32 v[226:227], v[204:205], v[126:127]
	v_pk_mul_f32 v[228:229], v[206:207], v[126:127]
	v_exp_f32_e32 v226, v226
	v_exp_f32_e32 v227, v227
	v_exp_f32_e32 v228, v228
	v_exp_f32_e32 v229, v229
	s_nop 0
	v_pk_add_f32 v[226:227], v[226:227], 1.0 op_sel_hi:[1,0]
	v_pk_add_f32 v[228:229], v[228:229], 1.0 op_sel_hi:[1,0]
	v_rcp_f32_e32 v226, v226
	v_rcp_f32_e32 v227, v227
	v_rcp_f32_e32 v228, v228
	v_rcp_f32_e32 v229, v229
	s_nop 0
	v_pk_mul_f32 v[204:205], v[204:205], v[226:227]
	v_pk_mul_f32 v[206:207], v[206:207], v[228:229]
	v_pk_mul_f32 v[204:205], v[204:205], v[112:113]
	v_pk_mul_f32 v[206:207], v[206:207], v[210:211]
	v_cvt_pk_bf16_f32 v122, v204, v205
	v_cvt_pk_bf16_f32 v123, v206, v207
	v_pk_fma_f32 v[204:205], v[148:149], v[160:161], v[156:157]
	v_pk_fma_f32 v[112:113], v[132:133], v[114:115], v[140:141]
	v_pk_fma_f32 v[206:207], v[150:151], v[162:163], v[158:159]
; __device__ __forceinline__ unsigned cvt_pk_bf16(float lo, float hi) { unsigned r; asm volatile("v_cvt_pk_bf16_f32 %0, %1, %2" : "=v"(r) : "v"(lo), "v"(hi)); return r; }
; __device__ __forceinline__ float fast_silu(float x) { return x * fast_sigmoid(x); }
; __device__ __forceinline__ float dpp_shr1(float old, float src) { return __int_as_float(__builtin_amdgcn_update_dpp(__float_as_int(old), __float_as_int(src), 0x111, 0xf, 0xf, false)); }
; __device__ __forceinline__ float dpp_shr2(float old, float src) { return __int_as_float(__builtin_amdgcn_update_dpp(__float_as_int(old), __float_as_int(src), 0x112, 0xf, 0xf, false)); }
; __device__ __forceinline__ float dpp_ror1(float src) { return __int_as_float(__builtin_amdgcn_mov_dpp(__float_as_int(src), 0x121, 0xf, 0xf, true)); }
;     __device__ __forceinline__ void operator()(const f32x4 (&acc)[2][2][4][2], const pg8::Unit& u, int wr, int wc, int fr, int fq) const {
;     ...
;             const f32x4 g0w = *(const f32x4*)(cw + jg), g1w = *(const f32x4*)(cw + UPW + jg), g2w = *(const f32x4*)(cw + 2 * UPW + jg), gb = *(const f32x4*)(cb + jg);
;             const f32x4 u0w = *(const f32x4*)(cw + DFF + jg), u1w = *(const f32x4*)(cw + UPW + DFF + jg), u2w = *(const f32x4*)(cw + 2 * UPW + DFF + jg), ub = *(const f32x4*)(cb + DFF + jg);
;     ...
;                 for (int m = 0; m < 4; ++m) {
;                     float a[4];
; #pragma unroll
;                     for (int e = 0; e < 4; ++e) {
;                         const float gc = acc[ai][0][m][n][e], uc = acc[ai][1][m][n][e];
;                         float og1, og2, ou1, ou2;
;                         if (m == 0) { og1 = pg1[e]; og2 = pg2[e]; ou1 = pu1[e]; ou2 = pu2[e]; }
;                         else { const float gp = acc[ai][0][m - 1][n][e], up = acc[ai][1][m - 1][n][e]; og1 = dpp_ror1(gp); og2 = dpp_ror2(gp); ou1 = dpp_ror1(up); ou2 = dpp_ror2(up); }
;                         const float gm1 = dpp_shr1(og1, gc), gm2 = dpp_shr2(og2, gc), um1 = dpp_shr1(ou1, uc), um2 = dpp_shr2(ou2, uc);
;                         const float yg = g0w[e] * gm2 + g1w[e] * gm1 + g2w[e] * gc + gb[e];
;                         const float yu = u0w[e] * um2 + u1w[e] * um1 + u2w[e] * uc + ub[e];
;                         a[e] = fast_silu(yg) * yu;
;                     }
;                     u32x2 pk; pk.x = cvt_pk_bf16(a[0], a[1]); pk.y = cvt_pk_bf16(a[2], a[3]);
	v_pk_fma_f32 v[210:211], v[134:135], v[116:117], v[142:143]
	v_pk_fma_f32 v[204:205], v[152:153], v[172:173], v[204:205]
	v_pk_fma_f32 v[112:113], v[128:129], v[164:165], v[112:113]
	v_pk_fma_f32 v[206:207], v[154:155], v[174:175], v[206:207]
	v_pk_fma_f32 v[210:211], v[130:131], v[166:167], v[210:211]
	v_pk_fma_f32 v[204:205], v[144:145], v[176:177], v[204:205]
	v_pk_fma_f32 v[112:113], v[136:137], v[168:169], v[112:113]
	v_pk_fma_f32 v[206:207], v[146:147], v[178:179], v[206:207]
	v_pk_fma_f32 v[210:211], v[138:139], v[170:171], v[210:211]
	v_pk_mul_f32 v[226:227], v[204:205], v[126:127]
	v_pk_mul_f32 v[228:229], v[206:207], v[126:127]
	v_exp_f32_e32 v226, v226
	v_exp_f32_e32 v227, v227
	v_exp_f32_e32 v228, v228
	v_exp_f32_e32 v229, v229
	s_nop 0
	v_pk_add_f32 v[226:227], v[226:227], 1.0 op_sel_hi:[1,0]
	v_pk_add_f32 v[228:229], v[228:229], 1.0 op_sel_hi:[1,0]
	v_rcp_f32_e32 v226, v226
	v_rcp_f32_e32 v227, v227
	v_rcp_f32_e32 v228, v228
	v_rcp_f32_e32 v229, v229
	s_nop 0
	v_pk_mul_f32 v[204:205], v[204:205], v[226:227]
	v_pk_mul_f32 v[206:207], v[206:207], v[228:229]
	v_pk_mul_f32 v[204:205], v[204:205], v[112:113]
	v_pk_mul_f32 v[206:207], v[206:207], v[210:211]
	v_cvt_pk_bf16_f32 v160, v204, v205
	v_cvt_pk_bf16_f32 v161, v206, v207
	global_load_dwordx4 v[114:117], v244, s[34:35] offset:16
	global_load_dwordx4 v[118:121], v244, s[86:87] offset:16
	global_load_dwordx4 v[100:103], v244, s[40:41] offset:16
	global_load_dwordx4 v[96:99], v244, s[42:43] offset:16
	global_load_dwordx4 v[230:233], v244, s[30:31] offset:16
	global_load_dwordx4 v[234:237], v244, s[38:39] offset:16
	global_load_dwordx4 v[238:241], v244, s[84:85] offset:16
	ds_read_b128 v[172:175], v215 offset:5120
	ds_read_b128 v[164:167], v215 offset:5632
	ds_read_b128 v[176:179], v215 offset:4096
	ds_read_b128 v[168:171], v215 offset:4608
	s_waitcnt lgkmcnt(0)
	v_mov_b32_dpp v172, v72 row_shr:1 row_mask:0xf bank_mask:0xf
	v_mov_b32_dpp v176, v76 row_shr:1 row_mask:0xf bank_mask:0xf
	v_mov_b32_dpp v164, v64 row_shr:1 row_mask:0xf bank_mask:0xf
	v_mov_b32_dpp v168, v68 row_shr:1 row_mask:0xf bank_mask:0xf
	v_mov_b32_dpp v173, v73 row_shr:1 row_mask:0xf bank_mask:0xf
	v_mov_b32_dpp v177, v77 row_shr:1 row_mask:0xf bank_mask:0xf
	v_mov_b32_dpp v165, v65 row_shr:1 row_mask:0xf bank_mask:0xf
	v_mov_b32_dpp v169, v69 row_shr:1 row_mask:0xf bank_mask:0xf
	v_mov_b32_dpp v174, v74 row_shr:1 row_mask:0xf bank_mask:0xf
	v_mov_b32_dpp v178, v78 row_shr:1 row_mask:0xf bank_mask:0xf
	v_mov_b32_dpp v166, v66 row_shr:1 row_mask:0xf bank_mask:0xf
	v_mov_b32_dpp v170, v70 row_shr:1 row_mask:0xf bank_mask:0xf
	v_mov_b32_dpp v175, v75 row_shr:1 row_mask:0xf bank_mask:0xf
	v_mov_b32_dpp v179, v79 row_shr:1 row_mask:0xf bank_mask:0xf
	v_mov_b32_dpp v167, v67 row_shr:1 row_mask:0xf bank_mask:0xf
	v_mov_b32_dpp v171, v71 row_shr:1 row_mask:0xf bank_mask:0xf
	v_pk_fma_f32 v[204:205], v[148:149], v[72:73], v[156:157]
	v_pk_fma_f32 v[112:113], v[132:133], v[64:65], v[140:141]
	v_pk_fma_f32 v[206:207], v[150:151], v[74:75], v[158:159]
	v_pk_fma_f32 v[210:211], v[134:135], v[66:67], v[142:143]
	v_pk_fma_f32 v[204:205], v[152:153], v[76:77], v[204:205]
	v_pk_fma_f32 v[112:113], v[128:129], v[68:69], v[112:113]
	v_pk_fma_f32 v[206:207], v[154:155], v[78:79], v[206:207]
	v_pk_fma_f32 v[210:211], v[130:131], v[70:71], v[210:211]
	v_pk_fma_f32 v[204:205], v[144:145], v[84:85], v[204:205]
	v_pk_fma_f32 v[112:113], v[136:137], v[80:81], v[112:113]
	v_pk_fma_f32 v[206:207], v[146:147], v[86:87], v[206:207]
	v_pk_fma_f32 v[210:211], v[138:139], v[82:83], v[210:211]
	v_pk_mul_f32 v[226:227], v[204:205], v[126:127]
	v_pk_mul_f32 v[228:229], v[206:207], v[126:127]
	v_exp_f32_e32 v226, v226
	v_exp_f32_e32 v227, v227
	v_exp_f32_e32 v228, v228
	v_exp_f32_e32 v229, v229
	s_nop 0
	v_pk_add_f32 v[226:227], v[226:227], 1.0 op_sel_hi:[1,0]
	v_pk_add_f32 v[228:229], v[228:229], 1.0 op_sel_hi:[1,0]
	v_rcp_f32_e32 v226, v226
	v_rcp_f32_e32 v227, v227
	v_rcp_f32_e32 v228, v228
	v_rcp_f32_e32 v229, v229
	s_nop 0
	v_pk_mul_f32 v[204:205], v[204:205], v[226:227]
	v_pk_mul_f32 v[206:207], v[206:207], v[228:229]
	v_pk_mul_f32 v[204:205], v[204:205], v[112:113]
	v_pk_mul_f32 v[206:207], v[206:207], v[210:211]
	v_cvt_pk_bf16_f32 v72, v204, v205
	v_cvt_pk_bf16_f32 v73, v206, v207
	v_pk_fma_f32 v[204:205], v[148:149], v[76:77], v[156:157]
	v_pk_fma_f32 v[112:113], v[132:133], v[68:69], v[140:141]
	v_pk_fma_f32 v[206:207], v[150:151], v[78:79], v[158:159]
	v_pk_fma_f32 v[210:211], v[134:135], v[70:71], v[142:143]
	v_pk_fma_f32 v[204:205], v[152:153], v[84:85], v[204:205]
	v_pk_fma_f32 v[112:113], v[128:129], v[80:81], v[112:113]
; #define LAS __attribute__((address_space(3)))
; __device__ __forceinline__ unsigned cvt_pk_bf16(float lo, float hi) { unsigned r; asm volatile("v_cvt_pk_bf16_f32 %0, %1, %2" : "=v"(r) : "v"(lo), "v"(hi)); return r; }
; __device__ __forceinline__ float fast_silu(float x) { return x * fast_sigmoid(x); }
; __device__ __forceinline__ float dpp_shr1(float old, float src) { return __int_as_float(__builtin_amdgcn_update_dpp(__float_as_int(old), __float_as_int(src), 0x111, 0xf, 0xf, false)); }
; __device__ __forceinline__ float dpp_shr2(float old, float src) { return __int_as_float(__builtin_amdgcn_update_dpp(__float_as_int(old), __float_as_int(src), 0x112, 0xf, 0xf, false)); }
;     __device__ __forceinline__ void operator()(const f32x4 (&acc)[2][2][4][2], const pg8::Unit& u, int wr, int wc, int fr, int fq) const {
;     ...
;                 if (gi > 0) {
;                     const LAS float* xp = xb + ((gi - 1) * 2) * 256 + cc0 + 4 * n;
;                     pg1 = *(const LAS f32x4*)(xp + 256); pu1 = *(const LAS f32x4*)(xp + 256 + 128);
;                     pg2 = *(const LAS f32x4*)(xp + (fr & 1) * 256); pu2 = *(const LAS f32x4*)(xp + (fr & 1) * 256 + 128);
;                 }
;     ...
;                 for (int m = 0; m < 4; ++m) {
;                     float a[4];
; #pragma unroll
;                     for (int e = 0; e < 4; ++e) {
;                         const float gc = acc[ai][0][m][n][e], uc = acc[ai][1][m][n][e];
;                         float og1, og2, ou1, ou2;
;                         if (m == 0) { og1 = pg1[e]; og2 = pg2[e]; ou1 = pu1[e]; ou2 = pu2[e]; }
;                         else { const float gp = acc[ai][0][m - 1][n][e], up = acc[ai][1][m - 1][n][e]; og1 = dpp_ror1(gp); og2 = dpp_ror2(gp); ou1 = dpp_ror1(up); ou2 = dpp_ror2(up); }
;                         const float gm1 = dpp_shr1(og1, gc), gm2 = dpp_shr2(og2, gc), um1 = dpp_shr1(ou1, uc), um2 = dpp_shr2(ou2, uc);
;                         const float yg = g0w[e] * gm2 + g1w[e] * gm1 + g2w[e] * gc + gb[e];
;                         const float yu = u0w[e] * um2 + u1w[e] * um1 + u2w[e] * uc + ub[e];
;                         a[e] = fast_silu(yg) * yu;
;                     }
;                     u32x2 pk; pk.x = cvt_pk_bf16(a[0], a[1]); pk.y = cvt_pk_bf16(a[2], a[3]);
	v_pk_fma_f32 v[206:207], v[154:155], v[86:87], v[206:207]
	v_pk_fma_f32 v[210:211], v[130:131], v[82:83], v[210:211]
	v_pk_fma_f32 v[204:205], v[144:145], v[92:93], v[204:205]
	v_pk_fma_f32 v[112:113], v[136:137], v[88:89], v[112:113]
	v_pk_fma_f32 v[206:207], v[146:147], v[94:95], v[206:207]
	v_pk_fma_f32 v[210:211], v[138:139], v[90:91], v[210:211]
	v_pk_mul_f32 v[226:227], v[204:205], v[126:127]
	v_pk_mul_f32 v[228:229], v[206:207], v[126:127]
	v_exp_f32_e32 v226, v226
	v_exp_f32_e32 v227, v227
	v_exp_f32_e32 v228, v228
	v_exp_f32_e32 v229, v229
	s_nop 0
	v_pk_add_f32 v[226:227], v[226:227], 1.0 op_sel_hi:[1,0]
	v_pk_add_f32 v[228:229], v[228:229], 1.0 op_sel_hi:[1,0]
	v_rcp_f32_e32 v226, v226
	v_rcp_f32_e32 v227, v227
	v_rcp_f32_e32 v228, v228
	v_rcp_f32_e32 v229, v229
	s_nop 0
	v_pk_mul_f32 v[204:205], v[204:205], v[226:227]
	v_pk_mul_f32 v[206:207], v[206:207], v[228:229]
	v_pk_mul_f32 v[204:205], v[204:205], v[112:113]
	v_pk_mul_f32 v[206:207], v[206:207], v[210:211]
	v_cvt_pk_bf16_f32 v76, v204, v205
	v_cvt_pk_bf16_f32 v77, v206, v207
	v_pk_fma_f32 v[204:205], v[148:149], v[84:85], v[156:157]
	v_pk_fma_f32 v[112:113], v[132:133], v[80:81], v[140:141]
	v_pk_fma_f32 v[206:207], v[150:151], v[86:87], v[158:159]
	v_pk_fma_f32 v[210:211], v[134:135], v[82:83], v[142:143]
	v_pk_fma_f32 v[204:205], v[152:153], v[92:93], v[204:205]
	v_pk_fma_f32 v[112:113], v[128:129], v[88:89], v[112:113]
	v_pk_fma_f32 v[206:207], v[154:155], v[94:95], v[206:207]
	v_pk_fma_f32 v[210:211], v[130:131], v[90:91], v[210:211]
	v_pk_fma_f32 v[204:205], v[144:145], v[172:173], v[204:205]
	v_pk_fma_f32 v[112:113], v[136:137], v[164:165], v[112:113]
	v_pk_fma_f32 v[206:207], v[146:147], v[174:175], v[206:207]
	v_pk_fma_f32 v[210:211], v[138:139], v[166:167], v[210:211]
	v_pk_mul_f32 v[226:227], v[204:205], v[126:127]
	v_pk_mul_f32 v[228:229], v[206:207], v[126:127]
	v_exp_f32_e32 v226, v226
	v_exp_f32_e32 v227, v227
	v_exp_f32_e32 v228, v228
	v_exp_f32_e32 v229, v229
	s_nop 0
	v_pk_add_f32 v[226:227], v[226:227], 1.0 op_sel_hi:[1,0]
	v_pk_add_f32 v[228:229], v[228:229], 1.0 op_sel_hi:[1,0]
	v_rcp_f32_e32 v226, v226
	v_rcp_f32_e32 v227, v227
	v_rcp_f32_e32 v228, v228
	v_rcp_f32_e32 v229, v229
	s_nop 0
	v_pk_mul_f32 v[204:205], v[204:205], v[226:227]
	v_pk_mul_f32 v[206:207], v[206:207], v[228:229]
	v_pk_mul_f32 v[204:205], v[204:205], v[112:113]
	v_pk_mul_f32 v[206:207], v[206:207], v[210:211]
	v_cvt_pk_bf16_f32 v84, v204, v205
	v_cvt_pk_bf16_f32 v85, v206, v207
	v_pk_fma_f32 v[204:205], v[148:149], v[92:93], v[156:157]
	v_pk_fma_f32 v[112:113], v[132:133], v[88:89], v[140:141]
	v_pk_fma_f32 v[206:207], v[150:151], v[94:95], v[158:159]
	v_pk_fma_f32 v[210:211], v[134:135], v[90:91], v[142:143]
	v_pk_fma_f32 v[204:205], v[152:153], v[172:173], v[204:205]
	v_pk_fma_f32 v[112:113], v[128:129], v[164:165], v[112:113]
	v_pk_fma_f32 v[206:207], v[154:155], v[174:175], v[206:207]
	v_pk_fma_f32 v[210:211], v[130:131], v[166:167], v[210:211]
	v_pk_fma_f32 v[204:205], v[144:145], v[176:177], v[204:205]
	v_pk_fma_f32 v[112:113], v[136:137], v[168:169], v[112:113]
	v_pk_fma_f32 v[206:207], v[146:147], v[178:179], v[206:207]
	v_pk_fma_f32 v[210:211], v[138:139], v[170:171], v[210:211]
	v_pk_mul_f32 v[226:227], v[204:205], v[126:127]
	v_pk_mul_f32 v[228:229], v[206:207], v[126:127]
	v_exp_f32_e32 v226, v226
	v_exp_f32_e32 v227, v227
	v_exp_f32_e32 v228, v228
	v_exp_f32_e32 v229, v229
	s_nop 0
	v_pk_add_f32 v[226:227], v[226:227], 1.0 op_sel_hi:[1,0]
	v_pk_add_f32 v[228:229], v[228:229], 1.0 op_sel_hi:[1,0]
	v_rcp_f32_e32 v226, v226
	v_rcp_f32_e32 v227, v227
	v_rcp_f32_e32 v228, v228
	v_rcp_f32_e32 v229, v229
	s_nop 0
	v_pk_mul_f32 v[204:205], v[204:205], v[226:227]
	v_pk_mul_f32 v[206:207], v[206:207], v[228:229]
	v_pk_mul_f32 v[204:205], v[204:205], v[112:113]
	v_pk_mul_f32 v[206:207], v[206:207], v[210:211]
	v_cvt_pk_bf16_f32 v92, v204, v205
	v_cvt_pk_bf16_f32 v93, v206, v207
	global_load_dwordx4 v[64:67], v244, s[36:37] offset:16
	v_mov_b32_e32 v172, 0
	v_mov_b32_e32 v173, 0
	v_mov_b32_e32 v174, 0
	v_mov_b32_e32 v175, 0
	v_mov_b32_e32 v164, 0
	v_mov_b32_e32 v165, 0
	v_mov_b32_e32 v166, 0
	v_mov_b32_e32 v167, 0
	v_mov_b32_e32 v176, 0
	v_mov_b32_e32 v177, 0
	v_mov_b32_e32 v178, 0
	v_mov_b32_e32 v179, 0
	v_mov_b32_e32 v168, 0
	v_mov_b32_e32 v169, 0
	v_mov_b32_e32 v170, 0
	v_mov_b32_e32 v171, 0
	s_andn2_b64 vcc, exec, s[24:25]
	s_cbranch_vccnz .Lupc2_nocarry10
	ds_read_b128 v[172:175], v215 offset:1040
	ds_read_b128 v[164:167], v215 offset:1552
	ds_read_b128 v[176:179], v215 offset:16
	ds_read_b128 v[168:171], v215 offset:528
